# cache policy: nt on the P6 gate-GEMM output stores (sigmoid gates into Z cols 0..2047, read once in P7)
# baseline (speedup 1.0000x reference)
; #define LAS __attribute__((address_space(3)))
; __device__ __forceinline__ unsigned cvt_pk_bf16(float lo, float hi) { f32x2_t v = {lo, hi}; bf16x2_t b = __builtin_convertvector(v, bf16x2_t); return __builtin_bit_cast(unsigned, b); }
; __device__ __forceinline__ float bflo(unsigned w) { return __uint_as_float(w << 16); }
; __device__ __forceinline__ float bfhi(unsigned w) { return __uint_as_float(w & 0xffff0000u); }
; __device__ __forceinline__ float sigm(float x) { return __builtin_amdgcn_rcpf(1.0f + __expf(-x)); }
;     __device__ __forceinline__ void operator()(AccRef acc, const pg8::Unit& u, int, int, int, int) const {
;     ...
;         for (int ai = 0; ai < 2; ++ai)
; #pragma unroll
;             for (int m = 0; m < 4; ++m) {
;                 const int row = row0 + ai * 128 + m * 16; float rs = 1.f;
;                 if (MODE == 1 || MODE == 4) rs = ((const LAS float*)((LAS unsigned char*)g_lds + pg8::RSL_OFF))[wid * 128 + ai * 64 + m * 16 + fr];
; #pragma unroll
;                 for (int bj = 0; bj < 2; ++bj) {
;                     const int col = col0 + bj * 128; float o[8];
; #pragma unroll
;                     for (int n = 0; n < 2; ++n)
; #pragma unroll
;                         for (int j = 0; j < 4; ++j) o[n * 4 + j] = acc[ai][bj][m][n][j] * rs;
;                     if (sg) {
; #pragma unroll
;                         for (int j = 0; j < 8; ++j) o[j] = sigm(o[j]); }
;                     if (MODE == 2 || MODE == 3) {
;                         const v4u x = *(const v4u*)(a1 + (size_t)row * ld1 + col);
;                         float xf[8] = {bflo(x.x), bfhi(x.x), bflo(x.y), bfhi(x.y), bflo(x.z), bfhi(x.z), bflo(x.w), bfhi(x.w)};
;                         if (MODE == 2) {
; #pragma unroll
;                             for (int j = 0; j < 8; ++j) o[j] *= xf[j]; }
;                         else { const v4u y = *(const v4u*)(a2 + (size_t)row * ld2 + col);
;                             float yf[8] = {bflo(y.x), bfhi(y.x), bflo(y.y), bfhi(y.y), bflo(y.z), bfhi(y.z), bflo(y.w), bfhi(y.w)};
; #pragma unroll
;                             for (int j = 0; j < 8; ++j) o[j] = xf[j] + yf[j] * o[j]; }
;                     }
;                     v4u w; w.x = cvt_pk_bf16(o[0], o[1]); w.y = cvt_pk_bf16(o[2], o[3]); w.z = cvt_pk_bf16(o[4], o[5]); w.w = cvt_pk_bf16(o[6], o[7]);
;                     *(v4u*)(O + (size_t)row * ldo + col) = w;
.LBB0_488:
	v_mov_b32_e32 v144, v155
	s_lshl_b32 s11, s34, 8
	v_readfirstlane_b32 s6, v144
	s_ashr_i32 s7, s6, 6
	s_lshl_b32 s18, s7, 5
	s_lshl_b32 s7, s7, 9
	v_and_b32_e32 v149, 15, v144
	s_add_i32 s7, s7, 0
	v_lshl_add_u32 v145, v149, 2, s7
	v_add_u32_e32 v145, 0x20000, v145
	ds_read2_b32 v[146:147], v145 offset1:16
	s_and_b32 s18, s18, 0x60
	s_ashr_i32 s6, s6, 2
	s_or_b32 s11, s18, s11
	v_lshrrev_b32_e32 v144, 1, v144
	s_waitcnt lgkmcnt(0)
	v_mul_f32_e32 v126, v126, v146
	v_mul_f32_e32 v127, v127, v146
	v_mul_f32_e32 v128, v128, v146
	v_mul_f32_e32 v129, v129, v146
	v_mul_f32_e32 v122, v122, v146
	v_mul_f32_e32 v123, v123, v146
	v_mul_f32_e32 v124, v124, v146
	v_mul_f32_e32 v126, 0xbfb8aa3b, v126
	v_mul_f32_e32 v127, 0xbfb8aa3b, v127
	v_mul_f32_e32 v125, v125, v146
	v_mul_f32_e32 v128, 0xbfb8aa3b, v128
	v_mul_f32_e32 v129, 0xbfb8aa3b, v129
	v_mul_f32_e32 v122, 0xbfb8aa3b, v122
	v_mul_f32_e32 v123, 0xbfb8aa3b, v123
	v_exp_f32_e32 v126, v126
	v_exp_f32_e32 v127, v127
	v_exp_f32_e32 v128, v128
	v_exp_f32_e32 v129, v129
	v_exp_f32_e32 v122, v122
	v_exp_f32_e32 v123, v123
	v_mul_f32_e32 v124, 0xbfb8aa3b, v124
	v_mul_f32_e32 v125, 0xbfb8aa3b, v125
	v_exp_f32_e32 v124, v124
	v_exp_f32_e32 v125, v125
	v_add_f32_e32 v126, 1.0, v126
	v_add_f32_e32 v127, 1.0, v127
	v_add_f32_e32 v128, 1.0, v128
	v_add_f32_e32 v129, 1.0, v129
	v_add_f32_e32 v122, 1.0, v122
	v_add_f32_e32 v123, 1.0, v123
	v_rcp_f32_e32 v126, v126
	v_rcp_f32_e32 v127, v127
	v_rcp_f32_e32 v128, v128
	v_rcp_f32_e32 v129, v129
	v_rcp_f32_e32 v122, v122
	v_rcp_f32_e32 v123, v123
	v_add_f32_e32 v124, 1.0, v124
	v_add_f32_e32 v125, 1.0, v125
	v_mul_f32_e32 v114, v114, v146
	s_andn2_b32 s6, s6, 63
	v_and_or_b32 v148, v144, 24, s11
	v_or_b32_e32 v144, s1, v149
	v_rcp_f32_e32 v124, v124
	v_rcp_f32_e32 v125, v125
	v_mul_f32_e32 v115, v115, v146
	v_mul_f32_e32 v114, 0xbfb8aa3b, v114
	v_add_u32_e32 v144, s6, v144
	v_readlane_b32 s6, v254, 43
	v_exp_f32_e32 v114, v114
	v_mul_f32_e32 v115, 0xbfb8aa3b, v115
	v_readlane_b32 s7, v254, 44
	v_exp_f32_e32 v115, v115
	v_cvt_pk_bf16_f32 v126, v126, v127
	v_cvt_pk_bf16_f32 v127, v128, v129
	v_cvt_pk_bf16_f32 v128, v122, v123
	v_mov_b64_e32 v[122:123], s[6:7]
	v_ashrrev_i32_e32 v149, 31, v148
	v_cvt_pk_bf16_f32 v129, v124, v125
	v_mad_i64_i32 v[150:151], s[6:7], v144, s68, v[122:123]
	v_lshlrev_b64 v[124:125], 1, v[148:149]
	v_lshl_add_u64 v[148:149], v[150:151], 0, v[124:125]
	v_mul_f32_e32 v116, v116, v146
	v_add_f32_e32 v114, 1.0, v114
	global_store_dwordx4 v[148:149], v[126:129], off nt
	v_mul_f32_e32 v118, v118, v146
	v_mul_f32_e32 v119, v119, v146
	v_mul_f32_e32 v120, v120, v146
	v_mul_f32_e32 v121, v121, v146
	v_mul_f32_e32 v117, v117, v146
	v_rcp_f32_e32 v126, v114
	v_add_f32_e32 v114, 1.0, v115
	v_mul_f32_e32 v115, 0xbfb8aa3b, v116
	v_mul_f32_e32 v118, 0xbfb8aa3b, v118
	v_mul_f32_e32 v119, 0xbfb8aa3b, v119
	v_mul_f32_e32 v120, 0xbfb8aa3b, v120
	v_mul_f32_e32 v121, 0xbfb8aa3b, v121
	v_exp_f32_e32 v115, v115
	v_mul_f32_e32 v116, 0xbfb8aa3b, v117
	v_exp_f32_e32 v118, v118
	v_exp_f32_e32 v119, v119
	v_exp_f32_e32 v120, v120
	v_exp_f32_e32 v121, v121
	v_exp_f32_e32 v116, v116
	v_rcp_f32_e32 v117, v114
	v_add_f32_e32 v114, 1.0, v115
	v_mul_f32_e32 v106, v106, v147
	v_add_f32_e32 v118, 1.0, v118
	v_add_f32_e32 v119, 1.0, v119
	v_add_f32_e32 v120, 1.0, v120
	v_add_f32_e32 v121, 1.0, v121
	v_rcp_f32_e32 v127, v114
	v_add_f32_e32 v114, 1.0, v116
	v_mul_f32_e32 v107, v107, v147
	v_mul_f32_e32 v106, 0xbfb8aa3b, v106
	v_rcp_f32_e32 v118, v118
	v_rcp_f32_e32 v119, v119
	v_rcp_f32_e32 v120, v120
	v_rcp_f32_e32 v121, v121
	v_rcp_f32_e32 v128, v114
	v_exp_f32_e32 v106, v106
	v_mul_f32_e32 v107, 0xbfb8aa3b, v107
	v_exp_f32_e32 v107, v107
	v_cvt_pk_bf16_f32 v114, v118, v119
	v_cvt_pk_bf16_f32 v115, v120, v121
	v_cvt_pk_bf16_f32 v116, v126, v117
	v_cvt_pk_bf16_f32 v117, v127, v128
	v_mul_f32_e32 v110, v110, v147
	v_mul_f32_e32 v111, v111, v147
	v_mul_f32_e32 v108, v108, v147
	v_add_f32_e32 v106, 1.0, v106
	global_store_dwordx4 v[148:149], v[114:117], off offset:256 nt
	v_mul_f32_e32 v112, v112, v147
	v_mul_f32_e32 v113, v113, v147
	v_mul_f32_e32 v110, 0xbfb8aa3b, v110
	v_mul_f32_e32 v111, 0xbfb8aa3b, v111
	v_mul_f32_e32 v109, v109, v147
	v_rcp_f32_e32 v115, v106
	v_add_f32_e32 v106, 1.0, v107
	v_mul_f32_e32 v107, 0xbfb8aa3b, v108
	v_exp_f32_e32 v110, v110
	v_exp_f32_e32 v111, v111
	v_mul_f32_e32 v112, 0xbfb8aa3b, v112
	v_mul_f32_e32 v113, 0xbfb8aa3b, v113
	v_exp_f32_e32 v107, v107
	v_mul_f32_e32 v108, 0xbfb8aa3b, v109
	v_exp_f32_e32 v112, v112
	v_exp_f32_e32 v113, v113
	v_exp_f32_e32 v108, v108
	v_add_f32_e32 v110, 1.0, v110
	v_add_f32_e32 v111, 1.0, v111
	v_rcp_f32_e32 v109, v106
	v_add_f32_e32 v106, 1.0, v107
	v_mul_f32_e32 v98, v98, v147
	v_rcp_f32_e32 v110, v110
	v_rcp_f32_e32 v111, v111
	v_add_f32_e32 v112, 1.0, v112
	v_add_f32_e32 v113, 1.0, v113
	v_rcp_f32_e32 v116, v106
	v_add_f32_e32 v106, 1.0, v108
	v_mul_f32_e32 v99, v99, v147
	v_mul_f32_e32 v98, 0xbfb8aa3b, v98
	v_rcp_f32_e32 v112, v112
	v_rcp_f32_e32 v113, v113
	v_rcp_f32_e32 v117, v106
	v_exp_f32_e32 v98, v98
	v_mul_f32_e32 v99, 0xbfb8aa3b, v99
	v_mul_f32_e32 v102, v102, v147
	v_mul_f32_e32 v103, v103, v147
	v_exp_f32_e32 v99, v99
	v_or_b32_e32 v114, 16, v144
	v_mul_f32_e32 v102, 0xbfb8aa3b, v102
	v_mul_f32_e32 v103, 0xbfb8aa3b, v103
	v_cvt_pk_bf16_f32 v106, v110, v111
	v_mad_i64_i32 v[110:111], s[6:7], v114, s68, v[122:123]
	v_exp_f32_e32 v102, v102
	v_exp_f32_e32 v103, v103
	v_cvt_pk_bf16_f32 v107, v112, v113
	v_cvt_pk_bf16_f32 v108, v115, v109
	v_cvt_pk_bf16_f32 v109, v116, v117
	v_lshl_add_u64 v[110:111], v[110:111], 0, v[124:125]
	v_mul_f32_e32 v100, v100, v147
	v_add_f32_e32 v98, 1.0, v98
	global_store_dwordx4 v[110:111], v[106:109], off nt
	v_mul_f32_e32 v101, v101, v147
	v_add_f32_e32 v102, 1.0, v102
	v_rcp_f32_e32 v106, v98
	v_add_f32_e32 v98, 1.0, v99
	v_mul_f32_e32 v99, 0xbfb8aa3b, v100
	v_exp_f32_e32 v99, v99
	v_mul_f32_e32 v100, 0xbfb8aa3b, v101
	v_add_f32_e32 v103, 1.0, v103
	v_exp_f32_e32 v100, v100
	v_rcp_f32_e32 v102, v102
	v_rcp_f32_e32 v103, v103
	v_rcp_f32_e32 v101, v98
	v_add_f32_e32 v98, 1.0, v99
	v_rcp_f32_e32 v107, v98
	v_add_f32_e32 v98, 1.0, v100
	v_mul_f32_e32 v104, v104, v147
	v_mul_f32_e32 v105, v105, v147
	v_rcp_f32_e32 v108, v98
	v_cvt_pk_bf16_f32 v98, v102, v103
	ds_read2_b32 v[102:103], v145 offset0:32 offset1:48
	v_mul_f32_e32 v104, 0xbfb8aa3b, v104
	v_mul_f32_e32 v105, 0xbfb8aa3b, v105
	v_exp_f32_e32 v104, v104
	v_exp_f32_e32 v105, v105
	s_waitcnt lgkmcnt(0)
; #define LAS __attribute__((address_space(3)))
; __device__ __forceinline__ unsigned cvt_pk_bf16(float lo, float hi) { f32x2_t v = {lo, hi}; bf16x2_t b = __builtin_convertvector(v, bf16x2_t); return __builtin_bit_cast(unsigned, b); }
; __device__ __forceinline__ float bflo(unsigned w) { return __uint_as_float(w << 16); }
; __device__ __forceinline__ float bfhi(unsigned w) { return __uint_as_float(w & 0xffff0000u); }
; __device__ __forceinline__ float sigm(float x) { return __builtin_amdgcn_rcpf(1.0f + __expf(-x)); }
;     __device__ __forceinline__ void operator()(AccRef acc, const pg8::Unit& u, int, int, int, int) const {
;     ...
;         for (int ai = 0; ai < 2; ++ai)
; #pragma unroll
;             for (int m = 0; m < 4; ++m) {
;                 const int row = row0 + ai * 128 + m * 16; float rs = 1.f;
;                 if (MODE == 1 || MODE == 4) rs = ((const LAS float*)((LAS unsigned char*)g_lds + pg8::RSL_OFF))[wid * 128 + ai * 64 + m * 16 + fr];
; #pragma unroll
;                 for (int bj = 0; bj < 2; ++bj) {
;                     const int col = col0 + bj * 128; float o[8];
; #pragma unroll
;                     for (int n = 0; n < 2; ++n)
; #pragma unroll
;                         for (int j = 0; j < 4; ++j) o[n * 4 + j] = acc[ai][bj][m][n][j] * rs;
;                     if (sg) {
; #pragma unroll
;                         for (int j = 0; j < 8; ++j) o[j] = sigm(o[j]); }
;                     if (MODE == 2 || MODE == 3) {
;                         const v4u x = *(const v4u*)(a1 + (size_t)row * ld1 + col);
;                         float xf[8] = {bflo(x.x), bfhi(x.x), bflo(x.y), bfhi(x.y), bflo(x.z), bfhi(x.z), bflo(x.w), bfhi(x.w)};
;                         if (MODE == 2) {
; #pragma unroll
;                             for (int j = 0; j < 8; ++j) o[j] *= xf[j]; }
;                         else { const v4u y = *(const v4u*)(a2 + (size_t)row * ld2 + col);
;                             float yf[8] = {bflo(y.x), bfhi(y.x), bflo(y.y), bfhi(y.y), bflo(y.z), bfhi(y.z), bflo(y.w), bfhi(y.w)};
; #pragma unroll
;                             for (int j = 0; j < 8; ++j) o[j] = xf[j] + yf[j] * o[j]; }
;                     }
;                     v4u w; w.x = cvt_pk_bf16(o[0], o[1]); w.y = cvt_pk_bf16(o[2], o[3]); w.z = cvt_pk_bf16(o[4], o[5]); w.w = cvt_pk_bf16(o[6], o[7]);
;                     *(v4u*)(O + (size_t)row * ldo + col) = w;
	v_mul_f32_e32 v90, v90, v102
	v_mul_f32_e32 v91, v91, v102
	v_add_f32_e32 v104, 1.0, v104
	v_add_f32_e32 v105, 1.0, v105
	v_mul_f32_e32 v90, 0xbfb8aa3b, v90
	v_rcp_f32_e32 v104, v104
	v_rcp_f32_e32 v105, v105
	v_exp_f32_e32 v90, v90
	v_mul_f32_e32 v91, 0xbfb8aa3b, v91
	v_exp_f32_e32 v91, v91
	v_cvt_pk_bf16_f32 v99, v104, v105
	v_cvt_pk_bf16_f32 v100, v106, v101
	v_cvt_pk_bf16_f32 v101, v107, v108
	v_mul_f32_e32 v94, v94, v102
	v_mul_f32_e32 v95, v95, v102
	v_mul_f32_e32 v92, v92, v102
	v_add_f32_e32 v90, 1.0, v90
	global_store_dwordx4 v[110:111], v[98:101], off offset:256 nt
	v_mul_f32_e32 v96, v96, v102
	v_mul_f32_e32 v97, v97, v102
	v_mul_f32_e32 v94, 0xbfb8aa3b, v94
	v_mul_f32_e32 v95, 0xbfb8aa3b, v95
	v_mul_f32_e32 v93, v93, v102
	v_rcp_f32_e32 v99, v90
	v_add_f32_e32 v90, 1.0, v91
	v_mul_f32_e32 v91, 0xbfb8aa3b, v92
	v_exp_f32_e32 v94, v94
	v_exp_f32_e32 v95, v95
	v_mul_f32_e32 v96, 0xbfb8aa3b, v96
	v_mul_f32_e32 v97, 0xbfb8aa3b, v97
	v_exp_f32_e32 v91, v91
	v_mul_f32_e32 v92, 0xbfb8aa3b, v93
	v_exp_f32_e32 v96, v96
	v_exp_f32_e32 v97, v97
	v_exp_f32_e32 v92, v92
	v_add_f32_e32 v94, 1.0, v94
	v_add_f32_e32 v95, 1.0, v95
	v_rcp_f32_e32 v93, v90
	v_add_f32_e32 v90, 1.0, v91
	v_mul_f32_e32 v82, v82, v102
	v_rcp_f32_e32 v94, v94
	v_rcp_f32_e32 v95, v95
	v_add_f32_e32 v96, 1.0, v96
	v_add_f32_e32 v97, 1.0, v97
	v_rcp_f32_e32 v100, v90
	v_add_f32_e32 v90, 1.0, v92
	v_mul_f32_e32 v83, v83, v102
	v_mul_f32_e32 v82, 0xbfb8aa3b, v82
	v_rcp_f32_e32 v96, v96
	v_rcp_f32_e32 v97, v97
	v_rcp_f32_e32 v101, v90
	v_exp_f32_e32 v82, v82
	v_mul_f32_e32 v83, 0xbfb8aa3b, v83
	v_exp_f32_e32 v83, v83
	v_or_b32_e32 v98, 32, v144
	v_cvt_pk_bf16_f32 v90, v94, v95
	v_mad_i64_i32 v[94:95], s[6:7], v98, s68, v[122:123]
	v_cvt_pk_bf16_f32 v91, v96, v97
	v_cvt_pk_bf16_f32 v92, v99, v93
	v_cvt_pk_bf16_f32 v93, v100, v101
	v_lshl_add_u64 v[94:95], v[94:95], 0, v[124:125]
	v_mul_f32_e32 v84, v84, v102
	v_add_f32_e32 v82, 1.0, v82
	global_store_dwordx4 v[94:95], v[90:93], off nt
	v_mul_f32_e32 v86, v86, v102
	v_mul_f32_e32 v87, v87, v102
	v_mul_f32_e32 v88, v88, v102
	v_mul_f32_e32 v89, v89, v102
	v_mul_f32_e32 v85, v85, v102
	v_rcp_f32_e32 v90, v82
	v_add_f32_e32 v82, 1.0, v83
	v_mul_f32_e32 v83, 0xbfb8aa3b, v84
	v_mul_f32_e32 v86, 0xbfb8aa3b, v86
	v_mul_f32_e32 v87, 0xbfb8aa3b, v87
	v_mul_f32_e32 v88, 0xbfb8aa3b, v88
	v_mul_f32_e32 v89, 0xbfb8aa3b, v89
	v_exp_f32_e32 v83, v83
	v_mul_f32_e32 v84, 0xbfb8aa3b, v85
	v_exp_f32_e32 v86, v86
	v_exp_f32_e32 v87, v87
	v_exp_f32_e32 v88, v88
	v_exp_f32_e32 v89, v89
	v_exp_f32_e32 v84, v84
	v_rcp_f32_e32 v85, v82
	v_add_f32_e32 v82, 1.0, v83
	v_mul_f32_e32 v74, v74, v103
	v_add_f32_e32 v86, 1.0, v86
	v_add_f32_e32 v87, 1.0, v87
	v_add_f32_e32 v88, 1.0, v88
	v_add_f32_e32 v89, 1.0, v89
	v_rcp_f32_e32 v91, v82
	v_add_f32_e32 v82, 1.0, v84
	v_mul_f32_e32 v75, v75, v103
	v_mul_f32_e32 v74, 0xbfb8aa3b, v74
	v_rcp_f32_e32 v86, v86
	v_rcp_f32_e32 v87, v87
	v_rcp_f32_e32 v88, v88
	v_rcp_f32_e32 v89, v89
	v_rcp_f32_e32 v92, v82
	v_exp_f32_e32 v74, v74
	v_mul_f32_e32 v75, 0xbfb8aa3b, v75
	v_exp_f32_e32 v75, v75
	v_cvt_pk_bf16_f32 v82, v86, v87
	v_cvt_pk_bf16_f32 v83, v88, v89
	v_cvt_pk_bf16_f32 v84, v90, v85
	v_cvt_pk_bf16_f32 v85, v91, v92
	v_mul_f32_e32 v78, v78, v103
	v_mul_f32_e32 v79, v79, v103
	v_mul_f32_e32 v76, v76, v103
	v_add_f32_e32 v74, 1.0, v74
	global_store_dwordx4 v[94:95], v[82:85], off offset:256 nt
	v_mul_f32_e32 v80, v80, v103
	v_mul_f32_e32 v81, v81, v103
	v_mul_f32_e32 v78, 0xbfb8aa3b, v78
	v_mul_f32_e32 v79, 0xbfb8aa3b, v79
	v_mul_f32_e32 v77, v77, v103
	v_rcp_f32_e32 v83, v74
	v_add_f32_e32 v74, 1.0, v75
	v_mul_f32_e32 v75, 0xbfb8aa3b, v76
	v_exp_f32_e32 v78, v78
	v_exp_f32_e32 v79, v79
	v_mul_f32_e32 v80, 0xbfb8aa3b, v80
	v_mul_f32_e32 v81, 0xbfb8aa3b, v81
	v_exp_f32_e32 v75, v75
	v_mul_f32_e32 v76, 0xbfb8aa3b, v77
	v_exp_f32_e32 v80, v80
	v_exp_f32_e32 v81, v81
	v_exp_f32_e32 v76, v76
	v_add_f32_e32 v78, 1.0, v78
	v_add_f32_e32 v79, 1.0, v79
	v_rcp_f32_e32 v77, v74
	v_add_f32_e32 v74, 1.0, v75
	v_mul_f32_e32 v66, v66, v103
	v_rcp_f32_e32 v78, v78
	v_rcp_f32_e32 v79, v79
	v_add_f32_e32 v80, 1.0, v80
	v_add_f32_e32 v81, 1.0, v81
	v_rcp_f32_e32 v84, v74
	v_add_f32_e32 v74, 1.0, v76
	v_mul_f32_e32 v67, v67, v103
	v_mul_f32_e32 v66, 0xbfb8aa3b, v66
	v_rcp_f32_e32 v80, v80
	v_rcp_f32_e32 v81, v81
	v_rcp_f32_e32 v85, v74
	v_exp_f32_e32 v66, v66
	v_mul_f32_e32 v67, 0xbfb8aa3b, v67
	v_mul_f32_e32 v70, v70, v103
	v_mul_f32_e32 v71, v71, v103
	v_exp_f32_e32 v67, v67
	v_or_b32_e32 v82, 48, v144
	v_mul_f32_e32 v70, 0xbfb8aa3b, v70
	v_mul_f32_e32 v71, 0xbfb8aa3b, v71
	v_cvt_pk_bf16_f32 v74, v78, v79
	v_mad_i64_i32 v[78:79], s[6:7], v82, s68, v[122:123]
	v_exp_f32_e32 v70, v70
	v_exp_f32_e32 v71, v71
	v_cvt_pk_bf16_f32 v75, v80, v81
	v_cvt_pk_bf16_f32 v76, v83, v77
	v_cvt_pk_bf16_f32 v77, v84, v85
	v_lshl_add_u64 v[78:79], v[78:79], 0, v[124:125]
	v_mul_f32_e32 v68, v68, v103
	v_add_f32_e32 v66, 1.0, v66
	global_store_dwordx4 v[78:79], v[74:77], off nt
	v_mul_f32_e32 v69, v69, v103
	v_add_f32_e32 v70, 1.0, v70
	v_rcp_f32_e32 v74, v66
	v_add_f32_e32 v66, 1.0, v67
	v_mul_f32_e32 v67, 0xbfb8aa3b, v68
	v_exp_f32_e32 v67, v67
	v_mul_f32_e32 v68, 0xbfb8aa3b, v69
	v_add_f32_e32 v71, 1.0, v71
	v_exp_f32_e32 v68, v68
	v_rcp_f32_e32 v70, v70
	v_rcp_f32_e32 v71, v71
	v_rcp_f32_e32 v69, v66
	v_add_f32_e32 v66, 1.0, v67
	v_rcp_f32_e32 v75, v66
	v_add_f32_e32 v66, 1.0, v68
	v_mul_f32_e32 v72, v72, v103
	v_mul_f32_e32 v73, v73, v103
	v_rcp_f32_e32 v76, v66
	v_cvt_pk_bf16_f32 v66, v70, v71
	ds_read2_b32 v[70:71], v145 offset0:64 offset1:80
	v_mul_f32_e32 v72, 0xbfb8aa3b, v72
	v_mul_f32_e32 v73, 0xbfb8aa3b, v73
	v_exp_f32_e32 v72, v72
	v_exp_f32_e32 v73, v73
	s_waitcnt lgkmcnt(0)
; #define LAS __attribute__((address_space(3)))
; __device__ __forceinline__ unsigned cvt_pk_bf16(float lo, float hi) { f32x2_t v = {lo, hi}; bf16x2_t b = __builtin_convertvector(v, bf16x2_t); return __builtin_bit_cast(unsigned, b); }
; __device__ __forceinline__ float bflo(unsigned w) { return __uint_as_float(w << 16); }
; __device__ __forceinline__ float bfhi(unsigned w) { return __uint_as_float(w & 0xffff0000u); }
; __device__ __forceinline__ float sigm(float x) { return __builtin_amdgcn_rcpf(1.0f + __expf(-x)); }
;     __device__ __forceinline__ void operator()(AccRef acc, const pg8::Unit& u, int, int, int, int) const {
;     ...
;         for (int ai = 0; ai < 2; ++ai)
; #pragma unroll
;             for (int m = 0; m < 4; ++m) {
;                 const int row = row0 + ai * 128 + m * 16; float rs = 1.f;
;                 if (MODE == 1 || MODE == 4) rs = ((const LAS float*)((LAS unsigned char*)g_lds + pg8::RSL_OFF))[wid * 128 + ai * 64 + m * 16 + fr];
; #pragma unroll
;                 for (int bj = 0; bj < 2; ++bj) {
;                     const int col = col0 + bj * 128; float o[8];
; #pragma unroll
;                     for (int n = 0; n < 2; ++n)
; #pragma unroll
;                         for (int j = 0; j < 4; ++j) o[n * 4 + j] = acc[ai][bj][m][n][j] * rs;
;                     if (sg) {
; #pragma unroll
;                         for (int j = 0; j < 8; ++j) o[j] = sigm(o[j]); }
;                     if (MODE == 2 || MODE == 3) {
;                         const v4u x = *(const v4u*)(a1 + (size_t)row * ld1 + col);
;                         float xf[8] = {bflo(x.x), bfhi(x.x), bflo(x.y), bfhi(x.y), bflo(x.z), bfhi(x.z), bflo(x.w), bfhi(x.w)};
;                         if (MODE == 2) {
; #pragma unroll
;                             for (int j = 0; j < 8; ++j) o[j] *= xf[j]; }
;                         else { const v4u y = *(const v4u*)(a2 + (size_t)row * ld2 + col);
;                             float yf[8] = {bflo(y.x), bfhi(y.x), bflo(y.y), bfhi(y.y), bflo(y.z), bfhi(y.z), bflo(y.w), bfhi(y.w)};
; #pragma unroll
;                             for (int j = 0; j < 8; ++j) o[j] = xf[j] + yf[j] * o[j]; }
;                     }
;                     v4u w; w.x = cvt_pk_bf16(o[0], o[1]); w.y = cvt_pk_bf16(o[2], o[3]); w.z = cvt_pk_bf16(o[4], o[5]); w.w = cvt_pk_bf16(o[6], o[7]);
;                     *(v4u*)(O + (size_t)row * ldo + col) = w;
	v_mul_f32_e32 v58, v58, v70
	v_mul_f32_e32 v59, v59, v70
	v_add_f32_e32 v72, 1.0, v72
	v_add_f32_e32 v73, 1.0, v73
	v_mul_f32_e32 v58, 0xbfb8aa3b, v58
	v_rcp_f32_e32 v72, v72
	v_rcp_f32_e32 v73, v73
	v_exp_f32_e32 v58, v58
	v_mul_f32_e32 v59, 0xbfb8aa3b, v59
	v_exp_f32_e32 v59, v59
	v_cvt_pk_bf16_f32 v67, v72, v73
	v_cvt_pk_bf16_f32 v68, v74, v69
	v_cvt_pk_bf16_f32 v69, v75, v76
	v_mul_f32_e32 v62, v62, v70
	v_mul_f32_e32 v63, v63, v70
	v_mul_f32_e32 v60, v60, v70
	v_add_f32_e32 v58, 1.0, v58
	global_store_dwordx4 v[78:79], v[66:69], off offset:256 nt
	v_mul_f32_e32 v64, v64, v70
	v_mul_f32_e32 v65, v65, v70
	v_mul_f32_e32 v62, 0xbfb8aa3b, v62
	v_mul_f32_e32 v63, 0xbfb8aa3b, v63
	v_mul_f32_e32 v61, v61, v70
	v_rcp_f32_e32 v67, v58
	v_add_f32_e32 v58, 1.0, v59
	v_mul_f32_e32 v59, 0xbfb8aa3b, v60
	v_exp_f32_e32 v62, v62
	v_exp_f32_e32 v63, v63
	v_mul_f32_e32 v64, 0xbfb8aa3b, v64
	v_mul_f32_e32 v65, 0xbfb8aa3b, v65
	v_exp_f32_e32 v59, v59
	v_mul_f32_e32 v60, 0xbfb8aa3b, v61
	v_exp_f32_e32 v64, v64
	v_exp_f32_e32 v65, v65
	v_exp_f32_e32 v60, v60
	v_add_f32_e32 v62, 1.0, v62
	v_add_f32_e32 v63, 1.0, v63
	v_rcp_f32_e32 v61, v58
	v_add_f32_e32 v58, 1.0, v59
	v_mul_f32_e32 v50, v50, v70
	v_rcp_f32_e32 v62, v62
	v_rcp_f32_e32 v63, v63
	v_add_f32_e32 v64, 1.0, v64
	v_add_f32_e32 v65, 1.0, v65
	v_rcp_f32_e32 v68, v58
	v_add_f32_e32 v58, 1.0, v60
	v_mul_f32_e32 v51, v51, v70
	v_mul_f32_e32 v50, 0xbfb8aa3b, v50
	v_rcp_f32_e32 v64, v64
	v_rcp_f32_e32 v65, v65
	v_rcp_f32_e32 v69, v58
	v_exp_f32_e32 v50, v50
	v_mul_f32_e32 v51, 0xbfb8aa3b, v51
	v_exp_f32_e32 v51, v51
	v_add_u32_e32 v66, 0x80, v144
	v_cvt_pk_bf16_f32 v58, v62, v63
	v_mad_i64_i32 v[62:63], s[6:7], v66, s68, v[122:123]
	v_cvt_pk_bf16_f32 v59, v64, v65
	v_cvt_pk_bf16_f32 v60, v67, v61
	v_cvt_pk_bf16_f32 v61, v68, v69
	v_lshl_add_u64 v[62:63], v[62:63], 0, v[124:125]
	v_mul_f32_e32 v52, v52, v70
	v_add_f32_e32 v50, 1.0, v50
	global_store_dwordx4 v[62:63], v[58:61], off nt
	v_mul_f32_e32 v54, v54, v70
	v_mul_f32_e32 v55, v55, v70
	v_mul_f32_e32 v56, v56, v70
	v_mul_f32_e32 v57, v57, v70
	v_mul_f32_e32 v53, v53, v70
	v_rcp_f32_e32 v58, v50
	v_add_f32_e32 v50, 1.0, v51
	v_mul_f32_e32 v51, 0xbfb8aa3b, v52
	v_mul_f32_e32 v54, 0xbfb8aa3b, v54
	v_mul_f32_e32 v55, 0xbfb8aa3b, v55
	v_mul_f32_e32 v56, 0xbfb8aa3b, v56
	v_mul_f32_e32 v57, 0xbfb8aa3b, v57
	v_exp_f32_e32 v51, v51
	v_mul_f32_e32 v52, 0xbfb8aa3b, v53
	v_exp_f32_e32 v54, v54
	v_exp_f32_e32 v55, v55
	v_exp_f32_e32 v56, v56
	v_exp_f32_e32 v57, v57
	v_exp_f32_e32 v52, v52
	v_rcp_f32_e32 v53, v50
	v_add_f32_e32 v50, 1.0, v51
	v_mul_f32_e32 v42, v42, v71
	v_add_f32_e32 v54, 1.0, v54
	v_add_f32_e32 v55, 1.0, v55
	v_add_f32_e32 v56, 1.0, v56
	v_add_f32_e32 v57, 1.0, v57
	v_rcp_f32_e32 v59, v50
	v_add_f32_e32 v50, 1.0, v52
	v_mul_f32_e32 v43, v43, v71
	v_mul_f32_e32 v42, 0xbfb8aa3b, v42
	v_rcp_f32_e32 v54, v54
	v_rcp_f32_e32 v55, v55
	v_rcp_f32_e32 v56, v56
	v_rcp_f32_e32 v57, v57
	v_rcp_f32_e32 v60, v50
	v_exp_f32_e32 v42, v42
	v_mul_f32_e32 v43, 0xbfb8aa3b, v43
	v_exp_f32_e32 v43, v43
	v_cvt_pk_bf16_f32 v50, v54, v55
	v_cvt_pk_bf16_f32 v51, v56, v57
	v_cvt_pk_bf16_f32 v52, v58, v53
	v_cvt_pk_bf16_f32 v53, v59, v60
	v_mul_f32_e32 v46, v46, v71
	v_mul_f32_e32 v47, v47, v71
	v_mul_f32_e32 v44, v44, v71
	v_add_f32_e32 v42, 1.0, v42
	global_store_dwordx4 v[62:63], v[50:53], off offset:256 nt
	v_mul_f32_e32 v48, v48, v71
	v_mul_f32_e32 v49, v49, v71
	v_mul_f32_e32 v46, 0xbfb8aa3b, v46
	v_mul_f32_e32 v47, 0xbfb8aa3b, v47
	v_mul_f32_e32 v45, v45, v71
	v_rcp_f32_e32 v51, v42
	v_add_f32_e32 v42, 1.0, v43
	v_mul_f32_e32 v43, 0xbfb8aa3b, v44
	v_exp_f32_e32 v46, v46
	v_exp_f32_e32 v47, v47
	v_mul_f32_e32 v48, 0xbfb8aa3b, v48
	v_mul_f32_e32 v49, 0xbfb8aa3b, v49
	v_exp_f32_e32 v43, v43
	v_mul_f32_e32 v44, 0xbfb8aa3b, v45
	v_exp_f32_e32 v48, v48
	v_exp_f32_e32 v49, v49
	v_exp_f32_e32 v44, v44
	v_add_f32_e32 v46, 1.0, v46
	v_add_f32_e32 v47, 1.0, v47
	v_rcp_f32_e32 v45, v42
	v_add_f32_e32 v42, 1.0, v43
	v_mul_f32_e32 v34, v34, v71
	v_rcp_f32_e32 v46, v46
	v_rcp_f32_e32 v47, v47
	v_add_f32_e32 v48, 1.0, v48
	v_add_f32_e32 v49, 1.0, v49
	v_rcp_f32_e32 v52, v42
	v_add_f32_e32 v42, 1.0, v44
	v_mul_f32_e32 v35, v35, v71
	v_mul_f32_e32 v34, 0xbfb8aa3b, v34
	v_rcp_f32_e32 v48, v48
	v_rcp_f32_e32 v49, v49
	v_rcp_f32_e32 v53, v42
	v_exp_f32_e32 v34, v34
	v_mul_f32_e32 v35, 0xbfb8aa3b, v35
	v_mul_f32_e32 v38, v38, v71
	v_mul_f32_e32 v39, v39, v71
	v_exp_f32_e32 v35, v35
	v_add_u32_e32 v50, 0x90, v144
	v_mul_f32_e32 v38, 0xbfb8aa3b, v38
	v_mul_f32_e32 v39, 0xbfb8aa3b, v39
	v_cvt_pk_bf16_f32 v42, v46, v47
	v_mad_i64_i32 v[46:47], s[6:7], v50, s68, v[122:123]
	v_exp_f32_e32 v38, v38
	v_exp_f32_e32 v39, v39
	v_cvt_pk_bf16_f32 v43, v48, v49
	v_cvt_pk_bf16_f32 v44, v51, v45
	v_cvt_pk_bf16_f32 v45, v52, v53
	v_lshl_add_u64 v[46:47], v[46:47], 0, v[124:125]
	v_mul_f32_e32 v36, v36, v71
	v_add_f32_e32 v34, 1.0, v34
	global_store_dwordx4 v[46:47], v[42:45], off nt
	v_mul_f32_e32 v37, v37, v71
	v_add_f32_e32 v38, 1.0, v38
	v_rcp_f32_e32 v42, v34
	v_add_f32_e32 v34, 1.0, v35
	v_mul_f32_e32 v35, 0xbfb8aa3b, v36
	v_exp_f32_e32 v35, v35
	v_mul_f32_e32 v36, 0xbfb8aa3b, v37
	v_add_f32_e32 v39, 1.0, v39
	v_exp_f32_e32 v36, v36
	v_rcp_f32_e32 v38, v38
	v_rcp_f32_e32 v39, v39
	v_rcp_f32_e32 v37, v34
	v_add_f32_e32 v34, 1.0, v35
	v_rcp_f32_e32 v43, v34
	v_add_f32_e32 v34, 1.0, v36
	v_mul_f32_e32 v40, v40, v71
	v_mul_f32_e32 v41, v41, v71
	v_rcp_f32_e32 v44, v34
	v_cvt_pk_bf16_f32 v34, v38, v39
	ds_read2_b32 v[38:39], v145 offset0:96 offset1:112
	v_mul_f32_e32 v40, 0xbfb8aa3b, v40
	v_mul_f32_e32 v41, 0xbfb8aa3b, v41
	v_exp_f32_e32 v40, v40
	v_exp_f32_e32 v41, v41
	s_waitcnt lgkmcnt(0)
; template <class Epi, bool ALIGN_EPI>
; __device__ __forceinline__ void gemm_phase(LAS unsigned char* lds, const Gemm g, const StaticOrder& S, const Epi& E) {
;     ...
;         if (!has_next) break;
; #pragma unroll
;         for (int a = 0; a < 2; ++a)
; #pragma unroll
;             for (int b = 0; b < 2; ++b)
; #pragma unroll
;                 for (int m = 0; m < 4; ++m)
; #pragma unroll
;                     for (int n = 0; n < 2; ++n) acc[a][b][m][n] = (f32x4){0.f, 0.f, 0.f, 0.f};
;         cur = nxt; cA = nA; cB = nB; ++ui;
;     __device__ __forceinline__ void operator()(AccRef acc, const pg8::Unit& u, int, int, int, int) const {
;     ...
;         for (int ai = 0; ai < 2; ++ai)
; #pragma unroll
;             for (int m = 0; m < 4; ++m) {
;                 const int row = row0 + ai * 128 + m * 16; float rs = 1.f;
;                 if (MODE == 1 || MODE == 4) rs = ((const LAS float*)((LAS unsigned char*)g_lds + pg8::RSL_OFF))[wid * 128 + ai * 64 + m * 16 + fr];
; #pragma unroll
;                 for (int bj = 0; bj < 2; ++bj) {
;                     const int col = col0 + bj * 128; float o[8];
; #pragma unroll
;                     for (int n = 0; n < 2; ++n)
; #pragma unroll
;                         for (int j = 0; j < 4; ++j) o[n * 4 + j] = acc[ai][bj][m][n][j] * rs;
;                     if (sg) {
; #pragma unroll
;                         for (int j = 0; j < 8; ++j) o[j] = sigm(o[j]); }
;                     if (MODE == 2 || MODE == 3) {
;                         const v4u x = *(const v4u*)(a1 + (size_t)row * ld1 + col);
;                         float xf[8] = {bflo(x.x), bfhi(x.x), bflo(x.y), bfhi(x.y), bflo(x.z), bfhi(x.z), bflo(x.w), bfhi(x.w)};
;                         if (MODE == 2) {
; #pragma unroll
;                             for (int j = 0; j < 8; ++j) o[j] *= xf[j]; }
;                         else { const v4u y = *(const v4u*)(a2 + (size_t)row * ld2 + col);
;                             float yf[8] = {bflo(y.x), bfhi(y.x), bflo(y.y), bfhi(y.y), bflo(y.z), bfhi(y.z), bflo(y.w), bfhi(y.w)};
; #pragma unroll
;                             for (int j = 0; j < 8; ++j) o[j] = xf[j] + yf[j] * o[j]; }
;                     }
;                     v4u w; w.x = cvt_pk_bf16(o[0], o[1]); w.y = cvt_pk_bf16(o[2], o[3]); w.z = cvt_pk_bf16(o[4], o[5]); w.w = cvt_pk_bf16(o[6], o[7]);
;                     *(v4u*)(O + (size_t)row * ldo + col) = w;
	v_mul_f32_e32 v26, v26, v38
	v_mul_f32_e32 v27, v27, v38
	v_add_f32_e32 v40, 1.0, v40
	v_add_f32_e32 v41, 1.0, v41
	v_mul_f32_e32 v26, 0xbfb8aa3b, v26
	v_rcp_f32_e32 v40, v40
	v_rcp_f32_e32 v41, v41
	v_exp_f32_e32 v26, v26
	v_mul_f32_e32 v27, 0xbfb8aa3b, v27
	v_exp_f32_e32 v27, v27
	v_cvt_pk_bf16_f32 v35, v40, v41
	v_cvt_pk_bf16_f32 v36, v42, v37
	v_cvt_pk_bf16_f32 v37, v43, v44
	v_mul_f32_e32 v30, v30, v38
	v_mul_f32_e32 v31, v31, v38
	v_mul_f32_e32 v28, v28, v38
	v_add_f32_e32 v26, 1.0, v26
	global_store_dwordx4 v[46:47], v[34:37], off offset:256 nt
	v_mul_f32_e32 v32, v32, v38
	v_mul_f32_e32 v33, v33, v38
	v_mul_f32_e32 v30, 0xbfb8aa3b, v30
	v_mul_f32_e32 v31, 0xbfb8aa3b, v31
	v_mul_f32_e32 v29, v29, v38
	v_rcp_f32_e32 v35, v26
	v_add_f32_e32 v26, 1.0, v27
	v_mul_f32_e32 v27, 0xbfb8aa3b, v28
	v_exp_f32_e32 v30, v30
	v_exp_f32_e32 v31, v31
	v_mul_f32_e32 v32, 0xbfb8aa3b, v32
	v_mul_f32_e32 v33, 0xbfb8aa3b, v33
	v_exp_f32_e32 v27, v27
	v_mul_f32_e32 v28, 0xbfb8aa3b, v29
	v_exp_f32_e32 v32, v32
	v_exp_f32_e32 v33, v33
	v_exp_f32_e32 v28, v28
	v_add_f32_e32 v30, 1.0, v30
	v_add_f32_e32 v31, 1.0, v31
	v_rcp_f32_e32 v29, v26
	v_add_f32_e32 v26, 1.0, v27
	v_mul_f32_e32 v18, v18, v38
	v_rcp_f32_e32 v30, v30
	v_rcp_f32_e32 v31, v31
	v_add_f32_e32 v32, 1.0, v32
	v_add_f32_e32 v33, 1.0, v33
	v_rcp_f32_e32 v36, v26
	v_add_f32_e32 v26, 1.0, v28
	v_mul_f32_e32 v19, v19, v38
	v_mul_f32_e32 v18, 0xbfb8aa3b, v18
	v_rcp_f32_e32 v32, v32
	v_rcp_f32_e32 v33, v33
	v_rcp_f32_e32 v37, v26
	v_exp_f32_e32 v18, v18
	v_mul_f32_e32 v19, 0xbfb8aa3b, v19
	v_exp_f32_e32 v19, v19
	v_add_u32_e32 v34, 0xa0, v144
	v_cvt_pk_bf16_f32 v26, v30, v31
	v_mad_i64_i32 v[30:31], s[6:7], v34, s68, v[122:123]
	v_cvt_pk_bf16_f32 v27, v32, v33
	v_cvt_pk_bf16_f32 v28, v35, v29
	v_cvt_pk_bf16_f32 v29, v36, v37
	v_lshl_add_u64 v[30:31], v[30:31], 0, v[124:125]
	v_mul_f32_e32 v20, v20, v38
	v_add_f32_e32 v18, 1.0, v18
	global_store_dwordx4 v[30:31], v[26:29], off nt
	v_mul_f32_e32 v22, v22, v38
	v_mul_f32_e32 v23, v23, v38
	v_mul_f32_e32 v24, v24, v38
	v_mul_f32_e32 v25, v25, v38
	v_mul_f32_e32 v21, v21, v38
	v_rcp_f32_e32 v26, v18
	v_add_f32_e32 v18, 1.0, v19
	v_mul_f32_e32 v19, 0xbfb8aa3b, v20
	v_mul_f32_e32 v22, 0xbfb8aa3b, v22
	v_mul_f32_e32 v23, 0xbfb8aa3b, v23
	v_mul_f32_e32 v24, 0xbfb8aa3b, v24
	v_mul_f32_e32 v25, 0xbfb8aa3b, v25
	v_exp_f32_e32 v19, v19
	v_mul_f32_e32 v20, 0xbfb8aa3b, v21
	v_exp_f32_e32 v22, v22
	v_exp_f32_e32 v23, v23
	v_exp_f32_e32 v24, v24
	v_exp_f32_e32 v25, v25
	v_exp_f32_e32 v20, v20
	v_rcp_f32_e32 v21, v18
	v_add_f32_e32 v18, 1.0, v19
	v_mul_f32_e32 v10, v10, v39
	v_add_f32_e32 v22, 1.0, v22
	v_add_f32_e32 v23, 1.0, v23
	v_add_f32_e32 v24, 1.0, v24
	v_add_f32_e32 v25, 1.0, v25
	v_rcp_f32_e32 v27, v18
	v_add_f32_e32 v18, 1.0, v20
	v_mul_f32_e32 v11, v11, v39
	v_mul_f32_e32 v10, 0xbfb8aa3b, v10
	v_rcp_f32_e32 v22, v22
	v_rcp_f32_e32 v23, v23
	v_rcp_f32_e32 v24, v24
	v_rcp_f32_e32 v25, v25
	v_rcp_f32_e32 v28, v18
	v_exp_f32_e32 v10, v10
	v_mul_f32_e32 v11, 0xbfb8aa3b, v11
	v_exp_f32_e32 v11, v11
	v_cvt_pk_bf16_f32 v18, v22, v23
	v_cvt_pk_bf16_f32 v19, v24, v25
	v_cvt_pk_bf16_f32 v20, v26, v21
	v_cvt_pk_bf16_f32 v21, v27, v28
	v_mul_f32_e32 v14, v14, v39
	v_mul_f32_e32 v15, v15, v39
	v_mul_f32_e32 v12, v12, v39
	v_add_f32_e32 v10, 1.0, v10
	global_store_dwordx4 v[30:31], v[18:21], off offset:256 nt
	v_mul_f32_e32 v16, v16, v39
	v_mul_f32_e32 v17, v17, v39
	v_mul_f32_e32 v14, 0xbfb8aa3b, v14
	v_mul_f32_e32 v15, 0xbfb8aa3b, v15
	v_mul_f32_e32 v13, v13, v39
	v_rcp_f32_e32 v19, v10
	v_add_f32_e32 v10, 1.0, v11
	v_mul_f32_e32 v11, 0xbfb8aa3b, v12
	v_exp_f32_e32 v14, v14
	v_exp_f32_e32 v15, v15
	v_mul_f32_e32 v16, 0xbfb8aa3b, v16
	v_mul_f32_e32 v17, 0xbfb8aa3b, v17
	v_exp_f32_e32 v11, v11
	v_mul_f32_e32 v12, 0xbfb8aa3b, v13
	v_exp_f32_e32 v16, v16
	v_exp_f32_e32 v17, v17
	v_exp_f32_e32 v12, v12
	v_add_f32_e32 v14, 1.0, v14
	v_add_f32_e32 v15, 1.0, v15
	v_rcp_f32_e32 v13, v10
	v_add_f32_e32 v10, 1.0, v11
	v_mul_f32_e32 v2, v2, v39
	v_rcp_f32_e32 v14, v14
	v_rcp_f32_e32 v15, v15
	v_add_f32_e32 v16, 1.0, v16
	v_add_f32_e32 v17, 1.0, v17
	v_rcp_f32_e32 v20, v10
	v_add_f32_e32 v10, 1.0, v12
	v_mul_f32_e32 v3, v3, v39
	v_mul_f32_e32 v2, 0xbfb8aa3b, v2
	v_rcp_f32_e32 v16, v16
	v_rcp_f32_e32 v17, v17
	v_rcp_f32_e32 v21, v10
	v_exp_f32_e32 v2, v2
	v_mul_f32_e32 v3, 0xbfb8aa3b, v3
	v_exp_f32_e32 v3, v3
	v_add_u32_e32 v18, 0xb0, v144
	v_cvt_pk_bf16_f32 v10, v14, v15
	v_mad_i64_i32 v[14:15], s[6:7], v18, s68, v[122:123]
	v_cvt_pk_bf16_f32 v11, v16, v17
	v_cvt_pk_bf16_f32 v12, v19, v13
	v_cvt_pk_bf16_f32 v13, v20, v21
	v_lshl_add_u64 v[14:15], v[14:15], 0, v[124:125]
	v_mul_f32_e32 v4, v4, v39
	v_add_f32_e32 v2, 1.0, v2
	global_store_dwordx4 v[14:15], v[10:13], off nt
	v_mul_f32_e32 v6, v6, v39
	v_mul_f32_e32 v7, v7, v39
	v_mul_f32_e32 v8, v8, v39
	v_mul_f32_e32 v9, v9, v39
	v_mul_f32_e32 v5, v5, v39
	v_rcp_f32_e32 v10, v2
	v_add_f32_e32 v2, 1.0, v3
	v_mul_f32_e32 v3, 0xbfb8aa3b, v4
	v_mul_f32_e32 v6, 0xbfb8aa3b, v6
	v_mul_f32_e32 v7, 0xbfb8aa3b, v7
	v_mul_f32_e32 v8, 0xbfb8aa3b, v8
	v_mul_f32_e32 v9, 0xbfb8aa3b, v9
	v_exp_f32_e32 v3, v3
	v_mul_f32_e32 v4, 0xbfb8aa3b, v5
	v_exp_f32_e32 v6, v6
	v_exp_f32_e32 v7, v7
	v_exp_f32_e32 v8, v8
	v_exp_f32_e32 v9, v9
	v_exp_f32_e32 v4, v4
	v_rcp_f32_e32 v5, v2
	v_add_f32_e32 v2, 1.0, v3
	v_add_f32_e32 v6, 1.0, v6
	v_add_f32_e32 v7, 1.0, v7
	v_add_f32_e32 v8, 1.0, v8
	v_add_f32_e32 v9, 1.0, v9
	v_rcp_f32_e32 v11, v2
	v_add_f32_e32 v2, 1.0, v4
	v_rcp_f32_e32 v6, v6
	v_rcp_f32_e32 v7, v7
	v_rcp_f32_e32 v8, v8
	v_rcp_f32_e32 v9, v9
	v_rcp_f32_e32 v12, v2
	v_cvt_pk_bf16_f32 v2, v6, v7
	v_cvt_pk_bf16_f32 v4, v10, v5
	v_cvt_pk_bf16_f32 v3, v8, v9
	v_cvt_pk_bf16_f32 v5, v11, v12
	s_andn2_b64 vcc, exec, s[12:13]
	s_mov_b64 s[6:7], -1
	global_store_dwordx4 v[14:15], v[2:5], off offset:256 nt
	s_cbranch_vccnz .LBB0_475
	s_andn2_b64 vcc, exec, s[2:3]
	s_cbranch_vccnz .LBB0_474
	s_barrier
	s_branch .LBB0_474
